# K-loop LDS-DMA stage loads with sc0 (vector-L1 bypass policy)
# baseline (speedup 1.0000x reference)
.LBB0_288:
	s_add_u32 s30, s28, 0xfffc0080
	s_addc_u32 s31, s29, -1
	s_add_i32 s56, 0, 0x10000
	s_cmp_eq_u32 s55, 12
	s_cselect_b32 s35, s21, s31
	s_cselect_b32 s34, s36, s30
	s_cselect_b32 s31, s19, s39
	s_cselect_b32 s30, s37, s38
	s_add_i32 s58, 0, 0x14000
	ds_read_b128 v[142:145], v147
	ds_read_b128 v[158:161], v147 offset:1024
	ds_read_b128 v[162:165], v147 offset:2048
	ds_read_b128 v[166:169], v147 offset:3072
	ds_read_b128 v[170:173], v147 offset:16384
	ds_read_b128 v[174:177], v147 offset:17408
	ds_read_b128 v[178:181], v147 offset:18432
	ds_read_b128 v[182:185], v147 offset:19456
	s_add_i32 m0, s44, 0xc000
	ds_read_b128 v[186:189], v157
	ds_read_b128 v[190:193], v157 offset:1024
	ds_read_b128 v[194:197], v157 offset:2048
	ds_read_b128 v[198:201], v157 offset:3072
	ds_read_b128 v[202:205], v157 offset:4096
	ds_read_b128 v[206:209], v157 offset:5120
	ds_read_b128 v[220:223], v157 offset:6144
	global_load_lds_dwordx4 v140, s[28:29] sc0
	s_add_i32 m0, s44, 0xe000
	ds_read_b128 v[236:239], v157 offset:7168
	global_load_lds_dwordx4 v138, s[28:29] sc0
	s_waitcnt vmcnt(8)
	s_waitcnt lgkmcnt(0)
	s_barrier
	v_mfma_f32_16x16x32_bf16 v[126:129], v[142:145], v[186:189], v[126:129]
	v_mfma_f32_16x16x32_bf16 v[122:125], v[162:165], v[186:189], v[122:125]
	v_mfma_f32_16x16x32_bf16 v[110:113], v[142:145], v[194:197], v[110:113]
	v_mfma_f32_16x16x32_bf16 v[106:109], v[162:165], v[194:197], v[106:109]
	v_mfma_f32_16x16x32_bf16 v[94:97], v[142:145], v[202:205], v[94:97]
	v_mfma_f32_16x16x32_bf16 v[90:93], v[162:165], v[202:205], v[90:93]
	v_mfma_f32_16x16x32_bf16 v[78:81], v[142:145], v[220:223], v[78:81]
	v_mfma_f32_16x16x32_bf16 v[74:77], v[162:165], v[220:223], v[74:77]
	v_mfma_f32_16x16x32_bf16 v[126:129], v[158:161], v[190:193], v[126:129]
	v_mfma_f32_16x16x32_bf16 v[122:125], v[166:169], v[190:193], v[122:125]
	v_mfma_f32_16x16x32_bf16 v[110:113], v[158:161], v[198:201], v[110:113]
	v_mfma_f32_16x16x32_bf16 v[106:109], v[166:169], v[198:201], v[106:109]
	v_mfma_f32_16x16x32_bf16 v[94:97], v[158:161], v[206:209], v[94:97]
	v_mfma_f32_16x16x32_bf16 v[90:93], v[166:169], v[206:209], v[90:93]
	v_mfma_f32_16x16x32_bf16 v[78:81], v[158:161], v[236:239], v[78:81]
	v_mfma_f32_16x16x32_bf16 v[74:77], v[166:169], v[236:239], v[74:77]
	v_mfma_f32_16x16x32_bf16 v[118:121], v[170:173], v[186:189], v[118:121]
	v_mfma_f32_16x16x32_bf16 v[114:117], v[178:181], v[186:189], v[114:117]
	v_mfma_f32_16x16x32_bf16 v[102:105], v[170:173], v[194:197], v[102:105]
	v_mfma_f32_16x16x32_bf16 v[98:101], v[178:181], v[194:197], v[98:101]
	v_mfma_f32_16x16x32_bf16 v[86:89], v[170:173], v[202:205], v[86:89]
	v_mfma_f32_16x16x32_bf16 v[82:85], v[178:181], v[202:205], v[82:85]
	v_mfma_f32_16x16x32_bf16 v[70:73], v[170:173], v[220:223], v[70:73]
	v_mfma_f32_16x16x32_bf16 v[66:69], v[178:181], v[220:223], v[66:69]
	v_mfma_f32_16x16x32_bf16 v[118:121], v[174:177], v[190:193], v[118:121]
	v_mfma_f32_16x16x32_bf16 v[114:117], v[182:185], v[190:193], v[114:117]
	v_mfma_f32_16x16x32_bf16 v[102:105], v[174:177], v[198:201], v[102:105]
	v_mfma_f32_16x16x32_bf16 v[98:101], v[182:185], v[198:201], v[98:101]
	v_mfma_f32_16x16x32_bf16 v[86:89], v[174:177], v[206:209], v[86:89]
	v_mfma_f32_16x16x32_bf16 v[82:85], v[182:185], v[206:209], v[82:85]
	v_mfma_f32_16x16x32_bf16 v[70:73], v[174:177], v[236:239], v[70:73]
	v_mfma_f32_16x16x32_bf16 v[66:69], v[182:185], v[236:239], v[66:69]
	s_barrier
	s_add_i32 s56, s56, s27
	s_mov_b32 m0, s56
	ds_read_b128 v[186:189], v157 offset:16384
	ds_read_b128 v[190:193], v157 offset:17408
	ds_read_b128 v[194:197], v157 offset:18432
	ds_read_b128 v[198:201], v157 offset:19456
	global_load_lds_dwordx4 v132, s[30:31] sc0
	s_add_i32 m0, s56, 0x2000
	s_add_u32 s56, s30, 0x40000
	s_addc_u32 s57, s31, 0
	s_add_i32 s58, s58, s27
	global_load_lds_dwordx4 v136, s[30:31] sc0
	s_mov_b32 m0, s58
	ds_read_b128 v[202:205], v157 offset:20480
	global_load_lds_dwordx4 v132, s[56:57] sc0
	s_add_i32 m0, s58, 0x2000
	ds_read_b128 v[206:209], v157 offset:21504
	global_load_lds_dwordx4 v136, s[56:57] sc0
	s_mov_b32 m0, s44
	ds_read_b128 v[220:223], v157 offset:22528
	global_load_lds_dwordx4 v130, s[34:35] sc0
	s_mov_b32 m0, s45
	ds_read_b128 v[236:239], v157 offset:23552
	global_load_lds_dwordx4 v134, s[34:35] sc0
	s_waitcnt vmcnt(8)
	s_waitcnt lgkmcnt(0)
	s_barrier
	v_mfma_f32_16x16x32_bf16 v[62:65], v[142:145], v[186:189], v[62:65]
	v_mfma_f32_16x16x32_bf16 v[58:61], v[162:165], v[186:189], v[58:61]
	v_mfma_f32_16x16x32_bf16 v[46:49], v[142:145], v[194:197], v[46:49]
	v_mfma_f32_16x16x32_bf16 v[42:45], v[162:165], v[194:197], v[42:45]
	v_mfma_f32_16x16x32_bf16 v[30:33], v[142:145], v[202:205], v[30:33]
	v_mfma_f32_16x16x32_bf16 v[26:29], v[162:165], v[202:205], v[26:29]
	v_mfma_f32_16x16x32_bf16 v[14:17], v[142:145], v[220:223], v[14:17]
	v_mfma_f32_16x16x32_bf16 v[10:13], v[162:165], v[220:223], v[10:13]
	v_mfma_f32_16x16x32_bf16 v[62:65], v[158:161], v[190:193], v[62:65]
	v_mfma_f32_16x16x32_bf16 v[58:61], v[166:169], v[190:193], v[58:61]
	v_mfma_f32_16x16x32_bf16 v[46:49], v[158:161], v[198:201], v[46:49]
	v_mfma_f32_16x16x32_bf16 v[42:45], v[166:169], v[198:201], v[42:45]
	v_mfma_f32_16x16x32_bf16 v[30:33], v[158:161], v[206:209], v[30:33]
	v_mfma_f32_16x16x32_bf16 v[26:29], v[166:169], v[206:209], v[26:29]
	v_mfma_f32_16x16x32_bf16 v[14:17], v[158:161], v[236:239], v[14:17]
	v_mfma_f32_16x16x32_bf16 v[10:13], v[166:169], v[236:239], v[10:13]
	v_mfma_f32_16x16x32_bf16 v[54:57], v[170:173], v[186:189], v[54:57]
	v_mfma_f32_16x16x32_bf16 v[50:53], v[178:181], v[186:189], v[50:53]
	v_mfma_f32_16x16x32_bf16 v[38:41], v[170:173], v[194:197], v[38:41]
	v_mfma_f32_16x16x32_bf16 v[34:37], v[178:181], v[194:197], v[34:37]
	v_mfma_f32_16x16x32_bf16 v[22:25], v[170:173], v[202:205], v[22:25]
	v_mfma_f32_16x16x32_bf16 v[18:21], v[178:181], v[202:205], v[18:21]
	v_mfma_f32_16x16x32_bf16 v[6:9], v[170:173], v[220:223], v[6:9]
	v_mfma_f32_16x16x32_bf16 v[2:5], v[178:181], v[220:223], v[2:5]
	v_mfma_f32_16x16x32_bf16 v[54:57], v[174:177], v[190:193], v[54:57]
	v_mfma_f32_16x16x32_bf16 v[50:53], v[182:185], v[190:193], v[50:53]
	v_mfma_f32_16x16x32_bf16 v[38:41], v[174:177], v[198:201], v[38:41]
	v_mfma_f32_16x16x32_bf16 v[34:37], v[182:185], v[198:201], v[34:37]
	v_mfma_f32_16x16x32_bf16 v[22:25], v[174:177], v[206:209], v[22:25]
	v_mfma_f32_16x16x32_bf16 v[18:21], v[182:185], v[206:209], v[18:21]
	v_mfma_f32_16x16x32_bf16 v[6:9], v[174:177], v[236:239], v[6:9]
	v_mfma_f32_16x16x32_bf16 v[2:5], v[182:185], v[236:239], v[2:5]
	s_barrier
	s_add_i32 s56, 0, 0x18000
	s_add_i32 s57, 0, 0x1c000
	ds_read_b128 v[142:145], v147 offset:32768
	ds_read_b128 v[158:161], v147 offset:33792
	ds_read_b128 v[162:165], v147 offset:34816
	ds_read_b128 v[166:169], v147 offset:35840
	ds_read_b128 v[170:173], v147 offset:49152
	ds_read_b128 v[174:177], v147 offset:50176
	ds_read_b128 v[178:181], v147 offset:51200
	ds_read_b128 v[182:185], v147 offset:52224
	s_add_u32 s34, s34, 0x40000
	s_addc_u32 s35, s35, 0
	s_mov_b32 m0, s43
	ds_read_b128 v[186:189], v157 offset:32768
	ds_read_b128 v[190:193], v157 offset:33792
	ds_read_b128 v[194:197], v157 offset:34816
	ds_read_b128 v[198:201], v157 offset:35840
	ds_read_b128 v[202:205], v157 offset:36864
	ds_read_b128 v[206:209], v157 offset:37888
	ds_read_b128 v[220:223], v157 offset:38912
	global_load_lds_dwordx4 v130, s[34:35] sc0
	s_mov_b32 m0, s46
	ds_read_b128 v[236:239], v157 offset:39936
	global_load_lds_dwordx4 v134, s[34:35] sc0
	s_waitcnt vmcnt(8)
	s_waitcnt lgkmcnt(0)
	s_barrier
	v_mfma_f32_16x16x32_bf16 v[126:129], v[142:145], v[186:189], v[126:129]
	v_mfma_f32_16x16x32_bf16 v[122:125], v[162:165], v[186:189], v[122:125]
	v_mfma_f32_16x16x32_bf16 v[110:113], v[142:145], v[194:197], v[110:113]
	v_mfma_f32_16x16x32_bf16 v[106:109], v[162:165], v[194:197], v[106:109]
	v_mfma_f32_16x16x32_bf16 v[94:97], v[142:145], v[202:205], v[94:97]
	v_mfma_f32_16x16x32_bf16 v[90:93], v[162:165], v[202:205], v[90:93]
	v_mfma_f32_16x16x32_bf16 v[78:81], v[142:145], v[220:223], v[78:81]
	v_mfma_f32_16x16x32_bf16 v[74:77], v[162:165], v[220:223], v[74:77]
	v_mfma_f32_16x16x32_bf16 v[126:129], v[158:161], v[190:193], v[126:129]
	v_mfma_f32_16x16x32_bf16 v[122:125], v[166:169], v[190:193], v[122:125]
	v_mfma_f32_16x16x32_bf16 v[110:113], v[158:161], v[198:201], v[110:113]
	v_mfma_f32_16x16x32_bf16 v[106:109], v[166:169], v[198:201], v[106:109]
	v_mfma_f32_16x16x32_bf16 v[94:97], v[158:161], v[206:209], v[94:97]
	v_mfma_f32_16x16x32_bf16 v[90:93], v[166:169], v[206:209], v[90:93]
	v_mfma_f32_16x16x32_bf16 v[78:81], v[158:161], v[236:239], v[78:81]
	v_mfma_f32_16x16x32_bf16 v[74:77], v[166:169], v[236:239], v[74:77]
	v_mfma_f32_16x16x32_bf16 v[118:121], v[170:173], v[186:189], v[118:121]
	v_mfma_f32_16x16x32_bf16 v[114:117], v[178:181], v[186:189], v[114:117]
	v_mfma_f32_16x16x32_bf16 v[102:105], v[170:173], v[194:197], v[102:105]
	v_mfma_f32_16x16x32_bf16 v[98:101], v[178:181], v[194:197], v[98:101]
	v_mfma_f32_16x16x32_bf16 v[86:89], v[170:173], v[202:205], v[86:89]
	v_mfma_f32_16x16x32_bf16 v[82:85], v[178:181], v[202:205], v[82:85]
	v_mfma_f32_16x16x32_bf16 v[70:73], v[170:173], v[220:223], v[70:73]
	v_mfma_f32_16x16x32_bf16 v[66:69], v[178:181], v[220:223], v[66:69]
	v_mfma_f32_16x16x32_bf16 v[118:121], v[174:177], v[190:193], v[118:121]
	v_mfma_f32_16x16x32_bf16 v[114:117], v[182:185], v[190:193], v[114:117]
	v_mfma_f32_16x16x32_bf16 v[102:105], v[174:177], v[198:201], v[102:105]
	v_mfma_f32_16x16x32_bf16 v[98:101], v[182:185], v[198:201], v[98:101]
	v_mfma_f32_16x16x32_bf16 v[86:89], v[174:177], v[206:209], v[86:89]
	v_mfma_f32_16x16x32_bf16 v[82:85], v[182:185], v[206:209], v[82:85]
	v_mfma_f32_16x16x32_bf16 v[70:73], v[174:177], v[236:239], v[70:73]
	v_mfma_f32_16x16x32_bf16 v[66:69], v[182:185], v[236:239], v[66:69]
	s_barrier
	s_add_u32 s100, s34, 0xfffc0080
	s_addc_u32 s101, s35, -1
	s_add_u32 s30, s30, 0x80
	s_addc_u32 s31, s31, 0
	s_add_i32 s34, s56, s27
	s_mov_b32 m0, s34
	ds_read_b128 v[186:189], v157 offset:49152
	ds_read_b128 v[190:193], v157 offset:50176
	ds_read_b128 v[194:197], v157 offset:51200
	ds_read_b128 v[198:201], v157 offset:52224
	global_load_lds_dwordx4 v132, s[30:31] sc0
	s_add_i32 m0, s34, 0x2000
	s_add_i32 s34, s57, s27
	global_load_lds_dwordx4 v136, s[30:31] sc0
	s_add_u32 s30, s30, 0x40000
	s_addc_u32 s31, s31, 0
	s_mov_b32 m0, s34
	ds_read_b128 v[202:205], v157 offset:53248
	global_load_lds_dwordx4 v132, s[30:31] sc0
	s_add_i32 m0, s34, 0x2000
	ds_read_b128 v[206:209], v157 offset:54272
	global_load_lds_dwordx4 v136, s[30:31] sc0
	s_mov_b32 m0, s47
	ds_read_b128 v[220:223], v157 offset:55296
	global_load_lds_dwordx4 v130, s[100:101] sc0
	s_mov_b32 m0, s48
	ds_read_b128 v[236:239], v157 offset:56320
	global_load_lds_dwordx4 v134, s[100:101] sc0
	s_waitcnt vmcnt(8)
	s_waitcnt lgkmcnt(0)
	s_barrier
	v_mfma_f32_16x16x32_bf16 v[62:65], v[142:145], v[186:189], v[62:65]
	v_mfma_f32_16x16x32_bf16 v[58:61], v[162:165], v[186:189], v[58:61]
	v_mfma_f32_16x16x32_bf16 v[46:49], v[142:145], v[194:197], v[46:49]
	v_mfma_f32_16x16x32_bf16 v[42:45], v[162:165], v[194:197], v[42:45]
	v_mfma_f32_16x16x32_bf16 v[30:33], v[142:145], v[202:205], v[30:33]
	v_mfma_f32_16x16x32_bf16 v[26:29], v[162:165], v[202:205], v[26:29]
	v_mfma_f32_16x16x32_bf16 v[14:17], v[142:145], v[220:223], v[14:17]
	v_mfma_f32_16x16x32_bf16 v[10:13], v[162:165], v[220:223], v[10:13]
	v_mfma_f32_16x16x32_bf16 v[62:65], v[158:161], v[190:193], v[62:65]
	v_mfma_f32_16x16x32_bf16 v[58:61], v[166:169], v[190:193], v[58:61]
	v_mfma_f32_16x16x32_bf16 v[46:49], v[158:161], v[198:201], v[46:49]
	v_mfma_f32_16x16x32_bf16 v[42:45], v[166:169], v[198:201], v[42:45]
	v_mfma_f32_16x16x32_bf16 v[30:33], v[158:161], v[206:209], v[30:33]
	v_mfma_f32_16x16x32_bf16 v[26:29], v[166:169], v[206:209], v[26:29]
	v_mfma_f32_16x16x32_bf16 v[14:17], v[158:161], v[236:239], v[14:17]
	v_mfma_f32_16x16x32_bf16 v[10:13], v[166:169], v[236:239], v[10:13]
	v_mfma_f32_16x16x32_bf16 v[54:57], v[170:173], v[186:189], v[54:57]
	v_mfma_f32_16x16x32_bf16 v[50:53], v[178:181], v[186:189], v[50:53]
	v_mfma_f32_16x16x32_bf16 v[38:41], v[170:173], v[194:197], v[38:41]
	v_mfma_f32_16x16x32_bf16 v[34:37], v[178:181], v[194:197], v[34:37]
	v_mfma_f32_16x16x32_bf16 v[22:25], v[170:173], v[202:205], v[22:25]
	v_mfma_f32_16x16x32_bf16 v[18:21], v[178:181], v[202:205], v[18:21]
	v_mfma_f32_16x16x32_bf16 v[6:9], v[170:173], v[220:223], v[6:9]
	v_mfma_f32_16x16x32_bf16 v[2:5], v[178:181], v[220:223], v[2:5]
	v_mfma_f32_16x16x32_bf16 v[54:57], v[174:177], v[190:193], v[54:57]
	v_mfma_f32_16x16x32_bf16 v[50:53], v[182:185], v[190:193], v[50:53]
	v_mfma_f32_16x16x32_bf16 v[38:41], v[174:177], v[198:201], v[38:41]
	v_mfma_f32_16x16x32_bf16 v[34:37], v[182:185], v[198:201], v[34:37]
	v_mfma_f32_16x16x32_bf16 v[22:25], v[174:177], v[206:209], v[22:25]
	v_mfma_f32_16x16x32_bf16 v[18:21], v[182:185], v[206:209], v[18:21]
	v_mfma_f32_16x16x32_bf16 v[6:9], v[174:177], v[236:239], v[6:9]
	v_mfma_f32_16x16x32_bf16 v[2:5], v[182:185], v[236:239], v[2:5]
	s_barrier
	s_add_i32 s55, s55, 2
	s_add_u32 s38, s38, 0x100
	s_addc_u32 s39, s39, 0
	s_add_u32 s28, s28, 0x100
	s_addc_u32 s29, s29, 0
	s_cmp_gt_u32 s55, 13
	s_cbranch_scc0 .LBB0_288
	s_and_b64 vcc, exec, s[12:13]
	s_cbranch_vccz .LBB0_291
	s_barrier

.LBB0_363:
	s_add_u32 s34, s30, 0xfffc0080
	s_addc_u32 s35, s31, -1
	s_add_i32 s57, 0, 0x10000
	s_cmp_eq_u32 s56, 12
	s_cselect_b32 s37, s23, s35
	s_cselect_b32 s36, s39, s34
	s_cselect_b32 s35, s21, s43
	s_cselect_b32 s34, s40, s41
	s_add_i32 s60, 0, 0x14000
	ds_read_b128 v[142:145], v155
	ds_read_b128 v[168:171], v155 offset:1024
	ds_read_b128 v[172:175], v155 offset:2048
	ds_read_b128 v[176:179], v155 offset:3072
	ds_read_b128 v[180:183], v155 offset:16384
	ds_read_b128 v[184:187], v155 offset:17408
	ds_read_b128 v[188:191], v155 offset:18432
	ds_read_b128 v[192:195], v155 offset:19456
	s_add_i32 m0, s48, 0xc000
	ds_read_b128 v[196:199], v157
	ds_read_b128 v[200:203], v157 offset:1024
	ds_read_b128 v[204:207], v157 offset:2048
	ds_read_b128 v[220:223], v157 offset:3072
	ds_read_b128 v[236:239], v157 offset:4096
	ds_read_b128 v[240:243], v157 offset:5120
	ds_read_b128 v[244:247], v157 offset:6144
	global_load_lds_dwordx4 v140, s[30:31] sc0
	s_add_i32 m0, s48, 0xe000
	ds_read_b128 v[248:251], v157 offset:7168
	global_load_lds_dwordx4 v138, s[30:31] sc0
	s_waitcnt vmcnt(8)
	s_waitcnt lgkmcnt(0)
	s_barrier
	v_mfma_f32_16x16x32_bf16 v[126:129], v[142:145], v[196:199], v[126:129]
	v_mfma_f32_16x16x32_bf16 v[118:121], v[172:175], v[196:199], v[118:121]
	v_mfma_f32_16x16x32_bf16 v[110:113], v[142:145], v[204:207], v[110:113]
	v_mfma_f32_16x16x32_bf16 v[102:105], v[172:175], v[204:207], v[102:105]
	v_mfma_f32_16x16x32_bf16 v[94:97], v[142:145], v[236:239], v[94:97]
	v_mfma_f32_16x16x32_bf16 v[86:89], v[172:175], v[236:239], v[86:89]
	v_mfma_f32_16x16x32_bf16 v[78:81], v[142:145], v[244:247], v[78:81]
	v_mfma_f32_16x16x32_bf16 v[70:73], v[172:175], v[244:247], v[70:73]
	v_mfma_f32_16x16x32_bf16 v[126:129], v[168:171], v[200:203], v[126:129]
	v_mfma_f32_16x16x32_bf16 v[118:121], v[176:179], v[200:203], v[118:121]
	v_mfma_f32_16x16x32_bf16 v[110:113], v[168:171], v[220:223], v[110:113]
	v_mfma_f32_16x16x32_bf16 v[102:105], v[176:179], v[220:223], v[102:105]
	v_mfma_f32_16x16x32_bf16 v[94:97], v[168:171], v[240:243], v[94:97]
	v_mfma_f32_16x16x32_bf16 v[86:89], v[176:179], v[240:243], v[86:89]
	v_mfma_f32_16x16x32_bf16 v[78:81], v[168:171], v[248:251], v[78:81]
	v_mfma_f32_16x16x32_bf16 v[70:73], v[176:179], v[248:251], v[70:73]
	v_mfma_f32_16x16x32_bf16 v[122:125], v[180:183], v[196:199], v[122:125]
	v_mfma_f32_16x16x32_bf16 v[114:117], v[188:191], v[196:199], v[114:117]
	v_mfma_f32_16x16x32_bf16 v[106:109], v[180:183], v[204:207], v[106:109]
	v_mfma_f32_16x16x32_bf16 v[98:101], v[188:191], v[204:207], v[98:101]
	v_mfma_f32_16x16x32_bf16 v[90:93], v[180:183], v[236:239], v[90:93]
	v_mfma_f32_16x16x32_bf16 v[82:85], v[188:191], v[236:239], v[82:85]
	v_mfma_f32_16x16x32_bf16 v[74:77], v[180:183], v[244:247], v[74:77]
	v_mfma_f32_16x16x32_bf16 v[66:69], v[188:191], v[244:247], v[66:69]
	v_mfma_f32_16x16x32_bf16 v[122:125], v[184:187], v[200:203], v[122:125]
	v_mfma_f32_16x16x32_bf16 v[114:117], v[192:195], v[200:203], v[114:117]
	v_mfma_f32_16x16x32_bf16 v[106:109], v[184:187], v[220:223], v[106:109]
	v_mfma_f32_16x16x32_bf16 v[98:101], v[192:195], v[220:223], v[98:101]
	v_mfma_f32_16x16x32_bf16 v[90:93], v[184:187], v[240:243], v[90:93]
	v_mfma_f32_16x16x32_bf16 v[82:85], v[192:195], v[240:243], v[82:85]
	v_mfma_f32_16x16x32_bf16 v[74:77], v[184:187], v[248:251], v[74:77]
	v_mfma_f32_16x16x32_bf16 v[66:69], v[192:195], v[248:251], v[66:69]
	s_barrier
	s_add_i32 s57, s57, s44
	s_mov_b32 m0, s57
	ds_read_b128 v[196:199], v157 offset:16384
	ds_read_b128 v[200:203], v157 offset:17408
	ds_read_b128 v[204:207], v157 offset:18432
	ds_read_b128 v[220:223], v157 offset:19456
	global_load_lds_dwordx4 v134, s[34:35] sc0
	s_add_i32 m0, s57, 0x2000
	s_add_u32 s58, s34, 0x40000
	s_addc_u32 s59, s35, 0
	s_add_i32 s57, s60, s44
	global_load_lds_dwordx4 v130, s[34:35] sc0
	s_mov_b32 m0, s57
	ds_read_b128 v[236:239], v157 offset:20480
	global_load_lds_dwordx4 v134, s[58:59] sc0
	s_add_i32 m0, s57, 0x2000
	ds_read_b128 v[240:243], v157 offset:21504
	global_load_lds_dwordx4 v130, s[58:59] sc0
	s_mov_b32 m0, s48
	ds_read_b128 v[244:247], v157 offset:22528
	global_load_lds_dwordx4 v136, s[36:37] sc0
	s_mov_b32 m0, s49
	ds_read_b128 v[248:251], v157 offset:23552
	global_load_lds_dwordx4 v132, s[36:37] sc0
	s_waitcnt vmcnt(8)
	s_waitcnt lgkmcnt(0)
	s_barrier
	v_mfma_f32_16x16x32_bf16 v[62:65], v[142:145], v[196:199], v[62:65]
	v_mfma_f32_16x16x32_bf16 v[54:57], v[172:175], v[196:199], v[54:57]
	v_mfma_f32_16x16x32_bf16 v[46:49], v[142:145], v[204:207], v[46:49]
	v_mfma_f32_16x16x32_bf16 v[38:41], v[172:175], v[204:207], v[38:41]
	v_mfma_f32_16x16x32_bf16 v[30:33], v[142:145], v[236:239], v[30:33]
	v_mfma_f32_16x16x32_bf16 v[22:25], v[172:175], v[236:239], v[22:25]
	v_mfma_f32_16x16x32_bf16 v[14:17], v[142:145], v[244:247], v[14:17]
	v_mfma_f32_16x16x32_bf16 v[6:9], v[172:175], v[244:247], v[6:9]
	v_mfma_f32_16x16x32_bf16 v[62:65], v[168:171], v[200:203], v[62:65]
	v_mfma_f32_16x16x32_bf16 v[54:57], v[176:179], v[200:203], v[54:57]
	v_mfma_f32_16x16x32_bf16 v[46:49], v[168:171], v[220:223], v[46:49]
	v_mfma_f32_16x16x32_bf16 v[38:41], v[176:179], v[220:223], v[38:41]
	v_mfma_f32_16x16x32_bf16 v[30:33], v[168:171], v[240:243], v[30:33]
	v_mfma_f32_16x16x32_bf16 v[22:25], v[176:179], v[240:243], v[22:25]
	v_mfma_f32_16x16x32_bf16 v[14:17], v[168:171], v[248:251], v[14:17]
	v_mfma_f32_16x16x32_bf16 v[6:9], v[176:179], v[248:251], v[6:9]
	v_mfma_f32_16x16x32_bf16 v[58:61], v[180:183], v[196:199], v[58:61]
	v_mfma_f32_16x16x32_bf16 v[50:53], v[188:191], v[196:199], v[50:53]
	v_mfma_f32_16x16x32_bf16 v[42:45], v[180:183], v[204:207], v[42:45]
	v_mfma_f32_16x16x32_bf16 v[34:37], v[188:191], v[204:207], v[34:37]
	v_mfma_f32_16x16x32_bf16 v[26:29], v[180:183], v[236:239], v[26:29]
	v_mfma_f32_16x16x32_bf16 v[18:21], v[188:191], v[236:239], v[18:21]
	v_mfma_f32_16x16x32_bf16 v[10:13], v[180:183], v[244:247], v[10:13]
	v_mfma_f32_16x16x32_bf16 v[2:5], v[188:191], v[244:247], v[2:5]
	v_mfma_f32_16x16x32_bf16 v[58:61], v[184:187], v[200:203], v[58:61]
	v_mfma_f32_16x16x32_bf16 v[50:53], v[192:195], v[200:203], v[50:53]
	v_mfma_f32_16x16x32_bf16 v[42:45], v[184:187], v[220:223], v[42:45]
	v_mfma_f32_16x16x32_bf16 v[34:37], v[192:195], v[220:223], v[34:37]
	v_mfma_f32_16x16x32_bf16 v[26:29], v[184:187], v[240:243], v[26:29]
	v_mfma_f32_16x16x32_bf16 v[18:21], v[192:195], v[240:243], v[18:21]
	v_mfma_f32_16x16x32_bf16 v[10:13], v[184:187], v[248:251], v[10:13]
	v_mfma_f32_16x16x32_bf16 v[2:5], v[192:195], v[248:251], v[2:5]
	s_barrier
	s_add_i32 s57, 0, 0x18000
	s_add_i32 s58, 0, 0x1c000
	ds_read_b128 v[142:145], v155 offset:32768
	ds_read_b128 v[168:171], v155 offset:33792
	ds_read_b128 v[172:175], v155 offset:34816
	ds_read_b128 v[176:179], v155 offset:35840
	ds_read_b128 v[180:183], v155 offset:49152
	ds_read_b128 v[184:187], v155 offset:50176
	ds_read_b128 v[188:191], v155 offset:51200
	ds_read_b128 v[192:195], v155 offset:52224
	s_add_u32 s36, s36, 0x40000
	s_addc_u32 s37, s37, 0
	s_mov_b32 m0, s50
	ds_read_b128 v[196:199], v157 offset:32768
	ds_read_b128 v[200:203], v157 offset:33792
	ds_read_b128 v[204:207], v157 offset:34816
	ds_read_b128 v[220:223], v157 offset:35840
	ds_read_b128 v[236:239], v157 offset:36864
	ds_read_b128 v[240:243], v157 offset:37888
	ds_read_b128 v[244:247], v157 offset:38912
	global_load_lds_dwordx4 v136, s[36:37] sc0
	s_mov_b32 m0, s51
	ds_read_b128 v[248:251], v157 offset:39936
	global_load_lds_dwordx4 v132, s[36:37] sc0
	s_waitcnt vmcnt(8)
	s_waitcnt lgkmcnt(0)
	s_barrier
	v_mfma_f32_16x16x32_bf16 v[126:129], v[142:145], v[196:199], v[126:129]
	v_mfma_f32_16x16x32_bf16 v[118:121], v[172:175], v[196:199], v[118:121]
	v_mfma_f32_16x16x32_bf16 v[110:113], v[142:145], v[204:207], v[110:113]
	v_mfma_f32_16x16x32_bf16 v[102:105], v[172:175], v[204:207], v[102:105]
	v_mfma_f32_16x16x32_bf16 v[94:97], v[142:145], v[236:239], v[94:97]
	v_mfma_f32_16x16x32_bf16 v[86:89], v[172:175], v[236:239], v[86:89]
	v_mfma_f32_16x16x32_bf16 v[78:81], v[142:145], v[244:247], v[78:81]
	v_mfma_f32_16x16x32_bf16 v[70:73], v[172:175], v[244:247], v[70:73]
	v_mfma_f32_16x16x32_bf16 v[126:129], v[168:171], v[200:203], v[126:129]
	v_mfma_f32_16x16x32_bf16 v[118:121], v[176:179], v[200:203], v[118:121]
	v_mfma_f32_16x16x32_bf16 v[110:113], v[168:171], v[220:223], v[110:113]
	v_mfma_f32_16x16x32_bf16 v[102:105], v[176:179], v[220:223], v[102:105]
	v_mfma_f32_16x16x32_bf16 v[94:97], v[168:171], v[240:243], v[94:97]
	v_mfma_f32_16x16x32_bf16 v[86:89], v[176:179], v[240:243], v[86:89]
	v_mfma_f32_16x16x32_bf16 v[78:81], v[168:171], v[248:251], v[78:81]
	v_mfma_f32_16x16x32_bf16 v[70:73], v[176:179], v[248:251], v[70:73]
	v_mfma_f32_16x16x32_bf16 v[122:125], v[180:183], v[196:199], v[122:125]
	v_mfma_f32_16x16x32_bf16 v[114:117], v[188:191], v[196:199], v[114:117]
	v_mfma_f32_16x16x32_bf16 v[106:109], v[180:183], v[204:207], v[106:109]
	v_mfma_f32_16x16x32_bf16 v[98:101], v[188:191], v[204:207], v[98:101]
	v_mfma_f32_16x16x32_bf16 v[90:93], v[180:183], v[236:239], v[90:93]
	v_mfma_f32_16x16x32_bf16 v[82:85], v[188:191], v[236:239], v[82:85]
	v_mfma_f32_16x16x32_bf16 v[74:77], v[180:183], v[244:247], v[74:77]
	v_mfma_f32_16x16x32_bf16 v[66:69], v[188:191], v[244:247], v[66:69]
	v_mfma_f32_16x16x32_bf16 v[122:125], v[184:187], v[200:203], v[122:125]
	v_mfma_f32_16x16x32_bf16 v[114:117], v[192:195], v[200:203], v[114:117]
	v_mfma_f32_16x16x32_bf16 v[106:109], v[184:187], v[220:223], v[106:109]
	v_mfma_f32_16x16x32_bf16 v[98:101], v[192:195], v[220:223], v[98:101]
	v_mfma_f32_16x16x32_bf16 v[90:93], v[184:187], v[240:243], v[90:93]
	v_mfma_f32_16x16x32_bf16 v[82:85], v[192:195], v[240:243], v[82:85]
	v_mfma_f32_16x16x32_bf16 v[74:77], v[184:187], v[248:251], v[74:77]
	v_mfma_f32_16x16x32_bf16 v[66:69], v[192:195], v[248:251], v[66:69]
	s_barrier
	s_add_u32 s100, s36, 0xfffc0080
	s_addc_u32 s101, s37, -1
	s_add_i32 s36, s57, s44
	s_add_u32 s34, s34, 0x80
	s_mov_b32 m0, s36
	s_addc_u32 s35, s35, 0
	ds_read_b128 v[196:199], v157 offset:49152
	ds_read_b128 v[200:203], v157 offset:50176
	ds_read_b128 v[204:207], v157 offset:51200
	ds_read_b128 v[220:223], v157 offset:52224
	ds_read_b128 v[236:239], v157 offset:53248
	global_load_lds_dwordx4 v134, s[34:35] sc0
	s_add_i32 m0, s36, 0x2000
	s_add_i32 s36, s58, s44
	global_load_lds_dwordx4 v130, s[34:35] sc0
	s_mov_b32 m0, s36
	s_add_u32 s34, s34, 0x40000
	s_addc_u32 s35, s35, 0
	global_load_lds_dwordx4 v134, s[34:35] sc0
	s_add_i32 m0, s36, 0x2000
	ds_read_b128 v[240:243], v157 offset:54272
	global_load_lds_dwordx4 v130, s[34:35] sc0
	s_mov_b32 m0, s52
	ds_read_b128 v[244:247], v157 offset:55296
	global_load_lds_dwordx4 v136, s[100:101] sc0
	s_mov_b32 m0, s53
	ds_read_b128 v[248:251], v157 offset:56320
	global_load_lds_dwordx4 v132, s[100:101] sc0
	s_waitcnt vmcnt(8)
	s_waitcnt lgkmcnt(0)
	s_barrier
	v_mfma_f32_16x16x32_bf16 v[62:65], v[142:145], v[196:199], v[62:65]
	v_mfma_f32_16x16x32_bf16 v[54:57], v[172:175], v[196:199], v[54:57]
	v_mfma_f32_16x16x32_bf16 v[46:49], v[142:145], v[204:207], v[46:49]
	v_mfma_f32_16x16x32_bf16 v[38:41], v[172:175], v[204:207], v[38:41]
	v_mfma_f32_16x16x32_bf16 v[30:33], v[142:145], v[236:239], v[30:33]
	v_mfma_f32_16x16x32_bf16 v[22:25], v[172:175], v[236:239], v[22:25]
	v_mfma_f32_16x16x32_bf16 v[14:17], v[142:145], v[244:247], v[14:17]
	v_mfma_f32_16x16x32_bf16 v[6:9], v[172:175], v[244:247], v[6:9]
	v_mfma_f32_16x16x32_bf16 v[62:65], v[168:171], v[200:203], v[62:65]
	v_mfma_f32_16x16x32_bf16 v[54:57], v[176:179], v[200:203], v[54:57]
	v_mfma_f32_16x16x32_bf16 v[46:49], v[168:171], v[220:223], v[46:49]
	v_mfma_f32_16x16x32_bf16 v[38:41], v[176:179], v[220:223], v[38:41]
	v_mfma_f32_16x16x32_bf16 v[30:33], v[168:171], v[240:243], v[30:33]
	v_mfma_f32_16x16x32_bf16 v[22:25], v[176:179], v[240:243], v[22:25]
	v_mfma_f32_16x16x32_bf16 v[14:17], v[168:171], v[248:251], v[14:17]
	v_mfma_f32_16x16x32_bf16 v[6:9], v[176:179], v[248:251], v[6:9]
	v_mfma_f32_16x16x32_bf16 v[58:61], v[180:183], v[196:199], v[58:61]
	v_mfma_f32_16x16x32_bf16 v[50:53], v[188:191], v[196:199], v[50:53]
	v_mfma_f32_16x16x32_bf16 v[42:45], v[180:183], v[204:207], v[42:45]
	v_mfma_f32_16x16x32_bf16 v[34:37], v[188:191], v[204:207], v[34:37]
	v_mfma_f32_16x16x32_bf16 v[26:29], v[180:183], v[236:239], v[26:29]
	v_mfma_f32_16x16x32_bf16 v[18:21], v[188:191], v[236:239], v[18:21]
	v_mfma_f32_16x16x32_bf16 v[10:13], v[180:183], v[244:247], v[10:13]
	v_mfma_f32_16x16x32_bf16 v[2:5], v[188:191], v[244:247], v[2:5]
	v_mfma_f32_16x16x32_bf16 v[58:61], v[184:187], v[200:203], v[58:61]
	v_mfma_f32_16x16x32_bf16 v[50:53], v[192:195], v[200:203], v[50:53]
	v_mfma_f32_16x16x32_bf16 v[42:45], v[184:187], v[220:223], v[42:45]
	v_mfma_f32_16x16x32_bf16 v[34:37], v[192:195], v[220:223], v[34:37]
	v_mfma_f32_16x16x32_bf16 v[26:29], v[184:187], v[240:243], v[26:29]
	v_mfma_f32_16x16x32_bf16 v[18:21], v[192:195], v[240:243], v[18:21]
	v_mfma_f32_16x16x32_bf16 v[10:13], v[184:187], v[248:251], v[10:13]
	v_mfma_f32_16x16x32_bf16 v[2:5], v[192:195], v[248:251], v[2:5]
	s_barrier
	s_add_i32 s56, s56, 2
	s_add_u32 s41, s41, 0x100
	s_addc_u32 s43, s43, 0
	s_add_u32 s30, s30, 0x100
	s_addc_u32 s31, s31, 0
	s_cmp_gt_u32 s56, 13
	s_cbranch_scc0 .LBB0_363
	s_and_b64 vcc, exec, s[16:17]
	s_cbranch_vccz .LBB0_366
	s_barrier

.LBB0_476:
	s_add_i32 s63, s31, 2
	s_add_u32 s38, s28, s36
	s_addc_u32 s39, s29, s37
	s_add_u32 s64, s26, s36
	s_addc_u32 s65, s27, s37
	s_add_i32 s66, 0, 0x10000
	s_cmp_eq_u32 s59, s31
	s_cselect_b32 s39, s9, s39
	s_cselect_b32 s38, s8, s38
	s_cselect_b32 s65, s35, s65
	s_cselect_b32 s64, s34, s64
	s_add_i32 s31, 0, 0x14000
	ds_read_b128 v[148:151], v146
	ds_read_b128 v[152:155], v146 offset:1024
	ds_read_b128 v[156:159], v146 offset:2048
	ds_read_b128 v[160:163], v146 offset:3072
	ds_read_b128 v[164:167], v146 offset:16384
	ds_read_b128 v[168:171], v146 offset:17408
	ds_read_b128 v[172:175], v146 offset:18432
	ds_read_b128 v[176:179], v146 offset:19456
	s_add_i32 m0, s51, 0xc000
	ds_read_b128 v[180:183], v147
	ds_read_b128 v[184:187], v147 offset:1024
	ds_read_b128 v[188:191], v147 offset:2048
	ds_read_b128 v[192:195], v147 offset:3072
	ds_read_b128 v[196:199], v147 offset:4096
	ds_read_b128 v[200:203], v147 offset:5120
	ds_read_b128 v[204:207], v147 offset:6144
	global_load_lds_dwordx4 v142, s[28:29] sc0
	s_add_i32 m0, s51, 0xe000
	ds_read_b128 v[220:223], v147 offset:7168
	global_load_lds_dwordx4 v144, s[28:29] sc0
	s_waitcnt vmcnt(8)
	s_waitcnt lgkmcnt(0)
	s_barrier
	v_mfma_f32_16x16x32_bf16 v[126:129], v[148:151], v[180:183], v[126:129]
	v_mfma_f32_16x16x32_bf16 v[122:125], v[156:159], v[180:183], v[122:125]
	v_mfma_f32_16x16x32_bf16 v[110:113], v[148:151], v[188:191], v[110:113]
	v_mfma_f32_16x16x32_bf16 v[106:109], v[156:159], v[188:191], v[106:109]
	v_mfma_f32_16x16x32_bf16 v[94:97], v[148:151], v[196:199], v[94:97]
	v_mfma_f32_16x16x32_bf16 v[90:93], v[156:159], v[196:199], v[90:93]
	v_mfma_f32_16x16x32_bf16 v[78:81], v[148:151], v[204:207], v[78:81]
	v_mfma_f32_16x16x32_bf16 v[74:77], v[156:159], v[204:207], v[74:77]
	v_mfma_f32_16x16x32_bf16 v[126:129], v[152:155], v[184:187], v[126:129]
	v_mfma_f32_16x16x32_bf16 v[122:125], v[160:163], v[184:187], v[122:125]
	v_mfma_f32_16x16x32_bf16 v[110:113], v[152:155], v[192:195], v[110:113]
	v_mfma_f32_16x16x32_bf16 v[106:109], v[160:163], v[192:195], v[106:109]
	v_mfma_f32_16x16x32_bf16 v[94:97], v[152:155], v[200:203], v[94:97]
	v_mfma_f32_16x16x32_bf16 v[90:93], v[160:163], v[200:203], v[90:93]
	v_mfma_f32_16x16x32_bf16 v[78:81], v[152:155], v[220:223], v[78:81]
	v_mfma_f32_16x16x32_bf16 v[74:77], v[160:163], v[220:223], v[74:77]
	v_mfma_f32_16x16x32_bf16 v[118:121], v[164:167], v[180:183], v[118:121]
	v_mfma_f32_16x16x32_bf16 v[114:117], v[172:175], v[180:183], v[114:117]
	v_mfma_f32_16x16x32_bf16 v[102:105], v[164:167], v[188:191], v[102:105]
	v_mfma_f32_16x16x32_bf16 v[98:101], v[172:175], v[188:191], v[98:101]
	v_mfma_f32_16x16x32_bf16 v[86:89], v[164:167], v[196:199], v[86:89]
	v_mfma_f32_16x16x32_bf16 v[82:85], v[172:175], v[196:199], v[82:85]
	v_mfma_f32_16x16x32_bf16 v[70:73], v[164:167], v[204:207], v[70:73]
	v_mfma_f32_16x16x32_bf16 v[66:69], v[172:175], v[204:207], v[66:69]
	v_mfma_f32_16x16x32_bf16 v[118:121], v[168:171], v[184:187], v[118:121]
	v_mfma_f32_16x16x32_bf16 v[114:117], v[176:179], v[184:187], v[114:117]
	v_mfma_f32_16x16x32_bf16 v[102:105], v[168:171], v[192:195], v[102:105]
	v_mfma_f32_16x16x32_bf16 v[98:101], v[176:179], v[192:195], v[98:101]
	v_mfma_f32_16x16x32_bf16 v[86:89], v[168:171], v[200:203], v[86:89]
	v_mfma_f32_16x16x32_bf16 v[82:85], v[176:179], v[200:203], v[82:85]
	v_mfma_f32_16x16x32_bf16 v[70:73], v[168:171], v[220:223], v[70:73]
	v_mfma_f32_16x16x32_bf16 v[66:69], v[176:179], v[220:223], v[66:69]
	s_barrier
	s_add_i32 s66, s66, s47
	s_mov_b32 m0, s66
	ds_read_b128 v[180:183], v147 offset:16384
	ds_read_b128 v[184:187], v147 offset:17408
	ds_read_b128 v[188:191], v147 offset:18432
	ds_read_b128 v[192:195], v147 offset:19456
	global_load_lds_dwordx4 v132, s[64:65] sc0
	s_add_i32 m0, s66, 0x2000
	s_mov_b64 s[100:101], s[64:65]
	s_add_u32 s64, s64, s45
	s_addc_u32 s65, s65, 0
	s_add_i32 s31, s31, s47
	global_load_lds_dwordx4 v136, s[100:101] sc0
	s_mov_b32 m0, s31
	ds_read_b128 v[196:199], v147 offset:20480
	global_load_lds_dwordx4 v132, s[64:65] sc0
	s_add_i32 m0, s31, 0x2000
	ds_read_b128 v[200:203], v147 offset:21504
	global_load_lds_dwordx4 v136, s[64:65] sc0
	s_mov_b32 m0, s51
	ds_read_b128 v[204:207], v147 offset:22528
	global_load_lds_dwordx4 v130, s[38:39] sc0
	s_mov_b32 m0, s52
	ds_read_b128 v[220:223], v147 offset:23552
	global_load_lds_dwordx4 v134, s[38:39] sc0
	s_waitcnt vmcnt(8)
	s_waitcnt lgkmcnt(0)
	s_barrier
	v_mfma_f32_16x16x32_bf16 v[62:65], v[148:151], v[180:183], v[62:65]
	v_mfma_f32_16x16x32_bf16 v[58:61], v[156:159], v[180:183], v[58:61]
	v_mfma_f32_16x16x32_bf16 v[46:49], v[148:151], v[188:191], v[46:49]
	v_mfma_f32_16x16x32_bf16 v[42:45], v[156:159], v[188:191], v[42:45]
	v_mfma_f32_16x16x32_bf16 v[30:33], v[148:151], v[196:199], v[30:33]
	v_mfma_f32_16x16x32_bf16 v[26:29], v[156:159], v[196:199], v[26:29]
	v_mfma_f32_16x16x32_bf16 v[14:17], v[148:151], v[204:207], v[14:17]
	v_mfma_f32_16x16x32_bf16 v[10:13], v[156:159], v[204:207], v[10:13]
	v_mfma_f32_16x16x32_bf16 v[62:65], v[152:155], v[184:187], v[62:65]
	v_mfma_f32_16x16x32_bf16 v[58:61], v[160:163], v[184:187], v[58:61]
	v_mfma_f32_16x16x32_bf16 v[46:49], v[152:155], v[192:195], v[46:49]
	v_mfma_f32_16x16x32_bf16 v[42:45], v[160:163], v[192:195], v[42:45]
	v_mfma_f32_16x16x32_bf16 v[30:33], v[152:155], v[200:203], v[30:33]
	v_mfma_f32_16x16x32_bf16 v[26:29], v[160:163], v[200:203], v[26:29]
	v_mfma_f32_16x16x32_bf16 v[14:17], v[152:155], v[220:223], v[14:17]
	v_mfma_f32_16x16x32_bf16 v[10:13], v[160:163], v[220:223], v[10:13]
	v_mfma_f32_16x16x32_bf16 v[54:57], v[164:167], v[180:183], v[54:57]
	v_mfma_f32_16x16x32_bf16 v[50:53], v[172:175], v[180:183], v[50:53]
	v_mfma_f32_16x16x32_bf16 v[38:41], v[164:167], v[188:191], v[38:41]
	v_mfma_f32_16x16x32_bf16 v[34:37], v[172:175], v[188:191], v[34:37]
	v_mfma_f32_16x16x32_bf16 v[22:25], v[164:167], v[196:199], v[22:25]
	v_mfma_f32_16x16x32_bf16 v[18:21], v[172:175], v[196:199], v[18:21]
	v_mfma_f32_16x16x32_bf16 v[6:9], v[164:167], v[204:207], v[6:9]
	v_mfma_f32_16x16x32_bf16 v[2:5], v[172:175], v[204:207], v[2:5]
	v_mfma_f32_16x16x32_bf16 v[54:57], v[168:171], v[184:187], v[54:57]
	v_mfma_f32_16x16x32_bf16 v[50:53], v[176:179], v[184:187], v[50:53]
	v_mfma_f32_16x16x32_bf16 v[38:41], v[168:171], v[192:195], v[38:41]
	v_mfma_f32_16x16x32_bf16 v[34:37], v[176:179], v[192:195], v[34:37]
	v_mfma_f32_16x16x32_bf16 v[22:25], v[168:171], v[200:203], v[22:25]
	v_mfma_f32_16x16x32_bf16 v[18:21], v[176:179], v[200:203], v[18:21]
	v_mfma_f32_16x16x32_bf16 v[6:9], v[168:171], v[220:223], v[6:9]
	v_mfma_f32_16x16x32_bf16 v[2:5], v[176:179], v[220:223], v[2:5]
	s_barrier
	s_add_i32 s31, 0, 0x18000
	s_add_i32 s64, 0, 0x1c000
	ds_read_b128 v[148:151], v146 offset:32768
	ds_read_b128 v[152:155], v146 offset:33792
	ds_read_b128 v[156:159], v146 offset:34816
	ds_read_b128 v[160:163], v146 offset:35840
	ds_read_b128 v[164:167], v146 offset:49152
	ds_read_b128 v[168:171], v146 offset:50176
	ds_read_b128 v[172:175], v146 offset:51200
	ds_read_b128 v[176:179], v146 offset:52224
	s_add_u32 s38, s38, s45
	s_addc_u32 s39, s39, 0
	s_mov_b32 m0, s53
	ds_read_b128 v[180:183], v147 offset:32768
	ds_read_b128 v[184:187], v147 offset:33792
	ds_read_b128 v[188:191], v147 offset:34816
	ds_read_b128 v[192:195], v147 offset:35840
	ds_read_b128 v[196:199], v147 offset:36864
	ds_read_b128 v[200:203], v147 offset:37888
	ds_read_b128 v[204:207], v147 offset:38912
	global_load_lds_dwordx4 v130, s[38:39] sc0
	s_mov_b32 m0, s54
	ds_read_b128 v[220:223], v147 offset:39936
	global_load_lds_dwordx4 v134, s[38:39] sc0
	s_waitcnt vmcnt(8)
	s_waitcnt lgkmcnt(0)
	s_barrier
	v_mfma_f32_16x16x32_bf16 v[126:129], v[148:151], v[180:183], v[126:129]
	v_mfma_f32_16x16x32_bf16 v[122:125], v[156:159], v[180:183], v[122:125]
	v_mfma_f32_16x16x32_bf16 v[110:113], v[148:151], v[188:191], v[110:113]
	v_mfma_f32_16x16x32_bf16 v[106:109], v[156:159], v[188:191], v[106:109]
	v_mfma_f32_16x16x32_bf16 v[94:97], v[148:151], v[196:199], v[94:97]
	v_mfma_f32_16x16x32_bf16 v[90:93], v[156:159], v[196:199], v[90:93]
	v_mfma_f32_16x16x32_bf16 v[78:81], v[148:151], v[204:207], v[78:81]
	v_mfma_f32_16x16x32_bf16 v[74:77], v[156:159], v[204:207], v[74:77]
	v_mfma_f32_16x16x32_bf16 v[126:129], v[152:155], v[184:187], v[126:129]
	v_mfma_f32_16x16x32_bf16 v[122:125], v[160:163], v[184:187], v[122:125]
	v_mfma_f32_16x16x32_bf16 v[110:113], v[152:155], v[192:195], v[110:113]
	v_mfma_f32_16x16x32_bf16 v[106:109], v[160:163], v[192:195], v[106:109]
	v_mfma_f32_16x16x32_bf16 v[94:97], v[152:155], v[200:203], v[94:97]
	v_mfma_f32_16x16x32_bf16 v[90:93], v[160:163], v[200:203], v[90:93]
	v_mfma_f32_16x16x32_bf16 v[78:81], v[152:155], v[220:223], v[78:81]
	v_mfma_f32_16x16x32_bf16 v[74:77], v[160:163], v[220:223], v[74:77]
	v_mfma_f32_16x16x32_bf16 v[118:121], v[164:167], v[180:183], v[118:121]
	v_mfma_f32_16x16x32_bf16 v[114:117], v[172:175], v[180:183], v[114:117]
	v_mfma_f32_16x16x32_bf16 v[102:105], v[164:167], v[188:191], v[102:105]
	v_mfma_f32_16x16x32_bf16 v[98:101], v[172:175], v[188:191], v[98:101]
	v_mfma_f32_16x16x32_bf16 v[86:89], v[164:167], v[196:199], v[86:89]
	v_mfma_f32_16x16x32_bf16 v[82:85], v[172:175], v[196:199], v[82:85]
	v_mfma_f32_16x16x32_bf16 v[70:73], v[164:167], v[204:207], v[70:73]
	v_mfma_f32_16x16x32_bf16 v[66:69], v[172:175], v[204:207], v[66:69]
	v_mfma_f32_16x16x32_bf16 v[118:121], v[168:171], v[184:187], v[118:121]
	v_mfma_f32_16x16x32_bf16 v[114:117], v[176:179], v[184:187], v[114:117]
	v_mfma_f32_16x16x32_bf16 v[102:105], v[168:171], v[192:195], v[102:105]
	v_mfma_f32_16x16x32_bf16 v[98:101], v[176:179], v[192:195], v[98:101]
	v_mfma_f32_16x16x32_bf16 v[86:89], v[168:171], v[200:203], v[86:89]
	v_mfma_f32_16x16x32_bf16 v[82:85], v[176:179], v[200:203], v[82:85]
	v_mfma_f32_16x16x32_bf16 v[70:73], v[168:171], v[220:223], v[70:73]
	v_mfma_f32_16x16x32_bf16 v[66:69], v[176:179], v[220:223], v[66:69]
	s_barrier
	s_add_i32 s31, s31, s47
	s_add_u32 s100, s100, 0x80
	s_addc_u32 s101, s101, 0
	s_mov_b32 m0, s31
	ds_read_b128 v[180:183], v147 offset:49152
	ds_read_b128 v[184:187], v147 offset:50176
	ds_read_b128 v[188:191], v147 offset:51200
	ds_read_b128 v[192:195], v147 offset:52224
	global_load_lds_dwordx4 v132, s[100:101] sc0
	s_add_i32 m0, s31, 0x2000
	s_add_i32 s31, s64, s47
	global_load_lds_dwordx4 v136, s[100:101] sc0
	s_add_u32 s100, s100, s45
	s_addc_u32 s101, s101, 0
	s_mov_b32 m0, s31
	ds_read_b128 v[196:199], v147 offset:53248
	global_load_lds_dwordx4 v132, s[100:101] sc0
	s_add_i32 m0, s31, 0x2000
	ds_read_b128 v[200:203], v147 offset:54272
	global_load_lds_dwordx4 v136, s[100:101] sc0
	s_sub_u32 s38, s38, s45
	s_subb_u32 s39, s39, 0
	s_add_u32 s38, s38, 0x80
	s_addc_u32 s39, s39, 0
	s_mov_b32 m0, s57
	ds_read_b128 v[204:207], v147 offset:55296
	global_load_lds_dwordx4 v130, s[38:39] sc0
	s_mov_b32 m0, s58
	ds_read_b128 v[220:223], v147 offset:56320
	global_load_lds_dwordx4 v134, s[38:39] sc0
	s_waitcnt vmcnt(8)
	s_waitcnt lgkmcnt(0)
	s_barrier
	v_mfma_f32_16x16x32_bf16 v[62:65], v[148:151], v[180:183], v[62:65]
	v_mfma_f32_16x16x32_bf16 v[58:61], v[156:159], v[180:183], v[58:61]
	v_mfma_f32_16x16x32_bf16 v[46:49], v[148:151], v[188:191], v[46:49]
	v_mfma_f32_16x16x32_bf16 v[42:45], v[156:159], v[188:191], v[42:45]
	v_mfma_f32_16x16x32_bf16 v[30:33], v[148:151], v[196:199], v[30:33]
	v_mfma_f32_16x16x32_bf16 v[26:29], v[156:159], v[196:199], v[26:29]
	v_mfma_f32_16x16x32_bf16 v[14:17], v[148:151], v[204:207], v[14:17]
	v_mfma_f32_16x16x32_bf16 v[10:13], v[156:159], v[204:207], v[10:13]
	v_mfma_f32_16x16x32_bf16 v[62:65], v[152:155], v[184:187], v[62:65]
	v_mfma_f32_16x16x32_bf16 v[58:61], v[160:163], v[184:187], v[58:61]
	v_mfma_f32_16x16x32_bf16 v[46:49], v[152:155], v[192:195], v[46:49]
	v_mfma_f32_16x16x32_bf16 v[42:45], v[160:163], v[192:195], v[42:45]
	v_mfma_f32_16x16x32_bf16 v[30:33], v[152:155], v[200:203], v[30:33]
	v_mfma_f32_16x16x32_bf16 v[26:29], v[160:163], v[200:203], v[26:29]
	v_mfma_f32_16x16x32_bf16 v[14:17], v[152:155], v[220:223], v[14:17]
	v_mfma_f32_16x16x32_bf16 v[10:13], v[160:163], v[220:223], v[10:13]
	v_mfma_f32_16x16x32_bf16 v[54:57], v[164:167], v[180:183], v[54:57]
	v_mfma_f32_16x16x32_bf16 v[50:53], v[172:175], v[180:183], v[50:53]
	v_mfma_f32_16x16x32_bf16 v[38:41], v[164:167], v[188:191], v[38:41]
	v_mfma_f32_16x16x32_bf16 v[34:37], v[172:175], v[188:191], v[34:37]
	v_mfma_f32_16x16x32_bf16 v[22:25], v[164:167], v[196:199], v[22:25]
	v_mfma_f32_16x16x32_bf16 v[18:21], v[172:175], v[196:199], v[18:21]
	v_mfma_f32_16x16x32_bf16 v[6:9], v[164:167], v[204:207], v[6:9]
	v_mfma_f32_16x16x32_bf16 v[2:5], v[172:175], v[204:207], v[2:5]
	v_mfma_f32_16x16x32_bf16 v[54:57], v[168:171], v[184:187], v[54:57]
	v_mfma_f32_16x16x32_bf16 v[50:53], v[176:179], v[184:187], v[50:53]
	v_mfma_f32_16x16x32_bf16 v[38:41], v[168:171], v[192:195], v[38:41]
	v_mfma_f32_16x16x32_bf16 v[34:37], v[176:179], v[192:195], v[34:37]
	v_mfma_f32_16x16x32_bf16 v[22:25], v[168:171], v[200:203], v[22:25]
	v_mfma_f32_16x16x32_bf16 v[18:21], v[176:179], v[200:203], v[18:21]
	v_mfma_f32_16x16x32_bf16 v[6:9], v[168:171], v[220:223], v[6:9]
	v_mfma_f32_16x16x32_bf16 v[2:5], v[176:179], v[220:223], v[2:5]
	s_barrier
	s_add_u32 s36, s36, 0x100
	s_addc_u32 s37, s37, 0
	v_add_u32_e32 v144, 0x100, v144
	v_add_u32_e32 v142, 0x100, v142
	s_cmp_ge_u32 s63, s56
	s_mov_b32 s31, s63
	s_cbranch_scc0 .LBB0_476
	s_and_b64 vcc, exec, s[6:7]
	s_cbranch_vccnz .LBB0_464
	v_mov_b32_e32 v2, 0
	s_mov_b32 s55, s61
	s_mov_b32 s50, s62
	s_mov_b64 s[26:27], s[34:35]
	s_mov_b64 s[28:29], s[8:9]
	s_mov_b32 s60, s30
	v_mov_b32_e32 v3, v2
	v_mov_b32_e32 v4, v2
	v_mov_b32_e32 v5, v2
	v_mov_b32_e32 v6, v2
	v_mov_b32_e32 v7, v2
	v_mov_b32_e32 v8, v2
	v_mov_b32_e32 v9, v2
	v_mov_b32_e32 v18, v2
	v_mov_b32_e32 v19, v2
	v_mov_b32_e32 v20, v2
	v_mov_b32_e32 v21, v2
	v_mov_b32_e32 v22, v2
	v_mov_b32_e32 v23, v2
	v_mov_b32_e32 v24, v2
	v_mov_b32_e32 v25, v2
	v_mov_b32_e32 v34, v2
	v_mov_b32_e32 v35, v2
	v_mov_b32_e32 v36, v2
	v_mov_b32_e32 v37, v2
	v_mov_b32_e32 v38, v2
	v_mov_b32_e32 v39, v2
	v_mov_b32_e32 v40, v2
	v_mov_b32_e32 v41, v2
	v_mov_b32_e32 v50, v2
	v_mov_b32_e32 v51, v2
	v_mov_b32_e32 v52, v2
	v_mov_b32_e32 v53, v2
	v_mov_b32_e32 v54, v2
	v_mov_b32_e32 v55, v2
	v_mov_b32_e32 v56, v2
	v_mov_b32_e32 v57, v2
	v_mov_b32_e32 v10, v2
	v_mov_b32_e32 v11, v2
	v_mov_b32_e32 v12, v2
	v_mov_b32_e32 v13, v2
	v_mov_b32_e32 v14, v2
	v_mov_b32_e32 v15, v2
	v_mov_b32_e32 v16, v2
	v_mov_b32_e32 v17, v2
	v_mov_b32_e32 v26, v2
	v_mov_b32_e32 v27, v2
	v_mov_b32_e32 v28, v2
	v_mov_b32_e32 v29, v2
	v_mov_b32_e32 v30, v2
	v_mov_b32_e32 v31, v2
	v_mov_b32_e32 v32, v2
	v_mov_b32_e32 v33, v2
	v_mov_b32_e32 v42, v2
	v_mov_b32_e32 v43, v2
	v_mov_b32_e32 v44, v2
	v_mov_b32_e32 v45, v2
	v_mov_b32_e32 v46, v2
	v_mov_b32_e32 v47, v2
	v_mov_b32_e32 v48, v2
	v_mov_b32_e32 v49, v2
	v_mov_b32_e32 v58, v2
	v_mov_b32_e32 v59, v2
	v_mov_b32_e32 v60, v2
	v_mov_b32_e32 v61, v2
	v_mov_b32_e32 v62, v2
	v_mov_b32_e32 v63, v2
	v_mov_b32_e32 v64, v2
	v_mov_b32_e32 v65, v2
	v_mov_b32_e32 v66, v2
	v_mov_b32_e32 v67, v2
	v_mov_b32_e32 v68, v2
	v_mov_b32_e32 v69, v2
	v_mov_b32_e32 v70, v2
	v_mov_b32_e32 v71, v2
	v_mov_b32_e32 v72, v2
	v_mov_b32_e32 v73, v2
	v_mov_b32_e32 v82, v2
	v_mov_b32_e32 v83, v2
	v_mov_b32_e32 v84, v2
	v_mov_b32_e32 v85, v2
	v_mov_b32_e32 v86, v2
	v_mov_b32_e32 v87, v2
	v_mov_b32_e32 v88, v2
	v_mov_b32_e32 v89, v2
	v_mov_b32_e32 v98, v2
	v_mov_b32_e32 v99, v2
	v_mov_b32_e32 v100, v2
	v_mov_b32_e32 v101, v2
	v_mov_b32_e32 v102, v2
	v_mov_b32_e32 v103, v2
	v_mov_b32_e32 v104, v2
	v_mov_b32_e32 v105, v2
	v_mov_b32_e32 v114, v2
	v_mov_b32_e32 v115, v2
	v_mov_b32_e32 v116, v2
	v_mov_b32_e32 v117, v2
	v_mov_b32_e32 v118, v2
	v_mov_b32_e32 v119, v2
	v_mov_b32_e32 v120, v2
	v_mov_b32_e32 v121, v2
	v_mov_b32_e32 v74, v2
	v_mov_b32_e32 v75, v2
	v_mov_b32_e32 v76, v2
	v_mov_b32_e32 v77, v2
	v_mov_b32_e32 v78, v2
	v_mov_b32_e32 v79, v2
	v_mov_b32_e32 v80, v2
	v_mov_b32_e32 v81, v2
	v_mov_b32_e32 v90, v2
	v_mov_b32_e32 v91, v2
	v_mov_b32_e32 v92, v2
	v_mov_b32_e32 v93, v2
	v_mov_b32_e32 v94, v2
	v_mov_b32_e32 v95, v2
	v_mov_b32_e32 v96, v2
	v_mov_b32_e32 v97, v2
	v_mov_b32_e32 v106, v2
	v_mov_b32_e32 v107, v2
	v_mov_b32_e32 v108, v2
	v_mov_b32_e32 v109, v2
	v_mov_b32_e32 v110, v2
	v_mov_b32_e32 v111, v2
	v_mov_b32_e32 v112, v2
	v_mov_b32_e32 v113, v2
	v_mov_b32_e32 v122, v2
	v_mov_b32_e32 v123, v2
	v_mov_b32_e32 v124, v2
	v_mov_b32_e32 v125, v2
	v_mov_b32_e32 v126, v2
	v_mov_b32_e32 v127, v2
	v_mov_b32_e32 v128, v2
	v_mov_b32_e32 v129, v2
	s_branch .LBB0_464

.LBB0_640:
	s_add_u32 s22, s20, 0xfffc0080
	s_addc_u32 s23, s21, -1
	s_add_i32 s46, 0, 0x10000
	s_cmp_eq_u32 s45, 12
	s_cselect_b32 s25, s13, s23
	s_cselect_b32 s24, s19, s22
	s_cselect_b32 s23, s11, s44
	s_cselect_b32 s22, s41, s43
	s_add_i32 s48, 0, 0x14000
	ds_read_b128 v[164:167], v159
	ds_read_b128 v[168:171], v159 offset:1024
	ds_read_b128 v[172:175], v159 offset:2048
	ds_read_b128 v[176:179], v159 offset:3072
	ds_read_b128 v[180:183], v159 offset:16384
	ds_read_b128 v[184:187], v159 offset:17408
	ds_read_b128 v[188:191], v159 offset:18432
	ds_read_b128 v[192:195], v159 offset:19456
	s_add_i32 m0, s30, 0xc000
	ds_read_b128 v[196:199], v162
	ds_read_b128 v[200:203], v162 offset:1024
	ds_read_b128 v[204:207], v162 offset:2048
	ds_read_b128 v[220:223], v162 offset:3072
	ds_read_b128 v[236:239], v162 offset:4096
	ds_read_b128 v[240:243], v162 offset:5120
	ds_read_b128 v[244:247], v162 offset:6144
	global_load_lds_dwordx4 v140, s[20:21] sc0
	s_add_i32 m0, s30, 0xe000
	ds_read_b128 v[248:251], v162 offset:7168
	global_load_lds_dwordx4 v138, s[20:21] sc0
	s_waitcnt vmcnt(8)
	s_waitcnt lgkmcnt(0)
	s_barrier
	v_mfma_f32_16x16x32_bf16 v[126:129], v[164:167], v[196:199], v[126:129]
	v_mfma_f32_16x16x32_bf16 v[122:125], v[172:175], v[196:199], v[122:125]
	v_mfma_f32_16x16x32_bf16 v[118:121], v[164:167], v[204:207], v[118:121]
	v_mfma_f32_16x16x32_bf16 v[114:117], v[172:175], v[204:207], v[114:117]
	v_mfma_f32_16x16x32_bf16 v[110:113], v[164:167], v[236:239], v[110:113]
	v_mfma_f32_16x16x32_bf16 v[106:109], v[172:175], v[236:239], v[106:109]
	v_mfma_f32_16x16x32_bf16 v[102:105], v[164:167], v[244:247], v[102:105]
	v_mfma_f32_16x16x32_bf16 v[98:101], v[172:175], v[244:247], v[98:101]
	v_mfma_f32_16x16x32_bf16 v[126:129], v[168:171], v[200:203], v[126:129]
	v_mfma_f32_16x16x32_bf16 v[122:125], v[176:179], v[200:203], v[122:125]
	v_mfma_f32_16x16x32_bf16 v[118:121], v[168:171], v[220:223], v[118:121]
	v_mfma_f32_16x16x32_bf16 v[114:117], v[176:179], v[220:223], v[114:117]
	v_mfma_f32_16x16x32_bf16 v[110:113], v[168:171], v[240:243], v[110:113]
	v_mfma_f32_16x16x32_bf16 v[106:109], v[176:179], v[240:243], v[106:109]
	v_mfma_f32_16x16x32_bf16 v[102:105], v[168:171], v[248:251], v[102:105]
	v_mfma_f32_16x16x32_bf16 v[98:101], v[176:179], v[248:251], v[98:101]
	v_mfma_f32_16x16x32_bf16 v[94:97], v[180:183], v[196:199], v[94:97]
	v_mfma_f32_16x16x32_bf16 v[90:93], v[188:191], v[196:199], v[90:93]
	v_mfma_f32_16x16x32_bf16 v[86:89], v[180:183], v[204:207], v[86:89]
	v_mfma_f32_16x16x32_bf16 v[82:85], v[188:191], v[204:207], v[82:85]
	v_mfma_f32_16x16x32_bf16 v[78:81], v[180:183], v[236:239], v[78:81]
	v_mfma_f32_16x16x32_bf16 v[74:77], v[188:191], v[236:239], v[74:77]
	v_mfma_f32_16x16x32_bf16 v[70:73], v[180:183], v[244:247], v[70:73]
	v_mfma_f32_16x16x32_bf16 v[66:69], v[188:191], v[244:247], v[66:69]
	v_mfma_f32_16x16x32_bf16 v[94:97], v[184:187], v[200:203], v[94:97]
	v_mfma_f32_16x16x32_bf16 v[90:93], v[192:195], v[200:203], v[90:93]
	v_mfma_f32_16x16x32_bf16 v[86:89], v[184:187], v[220:223], v[86:89]
	v_mfma_f32_16x16x32_bf16 v[82:85], v[192:195], v[220:223], v[82:85]
	v_mfma_f32_16x16x32_bf16 v[78:81], v[184:187], v[240:243], v[78:81]
	v_mfma_f32_16x16x32_bf16 v[74:77], v[192:195], v[240:243], v[74:77]
	v_mfma_f32_16x16x32_bf16 v[70:73], v[184:187], v[248:251], v[70:73]
	v_mfma_f32_16x16x32_bf16 v[66:69], v[192:195], v[248:251], v[66:69]
	s_barrier
	s_add_i32 s46, s46, s28
	s_mov_b32 m0, s46
	ds_read_b128 v[196:199], v162 offset:16384
	ds_read_b128 v[200:203], v162 offset:17408
	ds_read_b128 v[204:207], v162 offset:18432
	ds_read_b128 v[220:223], v162 offset:19456
	global_load_lds_dwordx4 v134, s[22:23] sc0
	s_add_i32 m0, s46, 0x2000
	s_add_u32 s46, s22, 0x40000
	s_addc_u32 s47, s23, 0
	s_add_i32 s48, s48, s28
	global_load_lds_dwordx4 v130, s[22:23] sc0
	s_mov_b32 m0, s48
	ds_read_b128 v[236:239], v162 offset:20480
	global_load_lds_dwordx4 v134, s[46:47] sc0
	s_add_i32 m0, s48, 0x2000
	ds_read_b128 v[240:243], v162 offset:21504
	global_load_lds_dwordx4 v130, s[46:47] sc0
	s_mov_b32 m0, s30
	ds_read_b128 v[244:247], v162 offset:22528
	global_load_lds_dwordx4 v136, s[24:25] sc0
	s_mov_b32 m0, s31
	ds_read_b128 v[248:251], v162 offset:23552
	global_load_lds_dwordx4 v132, s[24:25] sc0
	s_waitcnt vmcnt(8)
	s_waitcnt lgkmcnt(0)
	s_barrier
	v_mfma_f32_16x16x32_bf16 v[62:65], v[164:167], v[196:199], v[62:65]
	v_mfma_f32_16x16x32_bf16 v[58:61], v[172:175], v[196:199], v[58:61]
	v_mfma_f32_16x16x32_bf16 v[54:57], v[164:167], v[204:207], v[54:57]
	v_mfma_f32_16x16x32_bf16 v[50:53], v[172:175], v[204:207], v[50:53]
	v_mfma_f32_16x16x32_bf16 v[46:49], v[164:167], v[236:239], v[46:49]
	v_mfma_f32_16x16x32_bf16 v[42:45], v[172:175], v[236:239], v[42:45]
	v_mfma_f32_16x16x32_bf16 v[38:41], v[164:167], v[244:247], v[38:41]
	v_mfma_f32_16x16x32_bf16 v[34:37], v[172:175], v[244:247], v[34:37]
	v_mfma_f32_16x16x32_bf16 v[62:65], v[168:171], v[200:203], v[62:65]
	v_mfma_f32_16x16x32_bf16 v[58:61], v[176:179], v[200:203], v[58:61]
	v_mfma_f32_16x16x32_bf16 v[54:57], v[168:171], v[220:223], v[54:57]
	v_mfma_f32_16x16x32_bf16 v[50:53], v[176:179], v[220:223], v[50:53]
	v_mfma_f32_16x16x32_bf16 v[46:49], v[168:171], v[240:243], v[46:49]
	v_mfma_f32_16x16x32_bf16 v[42:45], v[176:179], v[240:243], v[42:45]
	v_mfma_f32_16x16x32_bf16 v[38:41], v[168:171], v[248:251], v[38:41]
	v_mfma_f32_16x16x32_bf16 v[34:37], v[176:179], v[248:251], v[34:37]
	v_mfma_f32_16x16x32_bf16 v[30:33], v[180:183], v[196:199], v[30:33]
	v_mfma_f32_16x16x32_bf16 v[26:29], v[188:191], v[196:199], v[26:29]
	v_mfma_f32_16x16x32_bf16 v[22:25], v[180:183], v[204:207], v[22:25]
	v_mfma_f32_16x16x32_bf16 v[18:21], v[188:191], v[204:207], v[18:21]
	v_mfma_f32_16x16x32_bf16 v[14:17], v[180:183], v[236:239], v[14:17]
	v_mfma_f32_16x16x32_bf16 v[10:13], v[188:191], v[236:239], v[10:13]
	v_mfma_f32_16x16x32_bf16 v[6:9], v[180:183], v[244:247], v[6:9]
	v_mfma_f32_16x16x32_bf16 v[2:5], v[188:191], v[244:247], v[2:5]
	v_mfma_f32_16x16x32_bf16 v[30:33], v[184:187], v[200:203], v[30:33]
	v_mfma_f32_16x16x32_bf16 v[26:29], v[192:195], v[200:203], v[26:29]
	v_mfma_f32_16x16x32_bf16 v[22:25], v[184:187], v[220:223], v[22:25]
	v_mfma_f32_16x16x32_bf16 v[18:21], v[192:195], v[220:223], v[18:21]
	v_mfma_f32_16x16x32_bf16 v[14:17], v[184:187], v[240:243], v[14:17]
	v_mfma_f32_16x16x32_bf16 v[10:13], v[192:195], v[240:243], v[10:13]
	v_mfma_f32_16x16x32_bf16 v[6:9], v[184:187], v[248:251], v[6:9]
	v_mfma_f32_16x16x32_bf16 v[2:5], v[192:195], v[248:251], v[2:5]
	s_barrier
	s_add_i32 s46, 0, 0x18000
	s_add_i32 s47, 0, 0x1c000
	ds_read_b128 v[164:167], v159 offset:32768
	ds_read_b128 v[168:171], v159 offset:33792
	ds_read_b128 v[172:175], v159 offset:34816
	ds_read_b128 v[176:179], v159 offset:35840
	ds_read_b128 v[180:183], v159 offset:49152
	ds_read_b128 v[184:187], v159 offset:50176
	ds_read_b128 v[188:191], v159 offset:51200
	ds_read_b128 v[192:195], v159 offset:52224
	s_add_u32 s24, s24, 0x40000
	s_addc_u32 s25, s25, 0
	s_mov_b32 m0, s34
	ds_read_b128 v[196:199], v162 offset:32768
	ds_read_b128 v[200:203], v162 offset:33792
	ds_read_b128 v[204:207], v162 offset:34816
	ds_read_b128 v[220:223], v162 offset:35840
	ds_read_b128 v[236:239], v162 offset:36864
	ds_read_b128 v[240:243], v162 offset:37888
	ds_read_b128 v[244:247], v162 offset:38912
	global_load_lds_dwordx4 v136, s[24:25] sc0
	s_mov_b32 m0, s35
	ds_read_b128 v[248:251], v162 offset:39936
	global_load_lds_dwordx4 v132, s[24:25] sc0
	s_waitcnt vmcnt(8)
	s_waitcnt lgkmcnt(0)
	s_barrier
	v_mfma_f32_16x16x32_bf16 v[126:129], v[164:167], v[196:199], v[126:129]
	v_mfma_f32_16x16x32_bf16 v[122:125], v[172:175], v[196:199], v[122:125]
	v_mfma_f32_16x16x32_bf16 v[118:121], v[164:167], v[204:207], v[118:121]
	v_mfma_f32_16x16x32_bf16 v[114:117], v[172:175], v[204:207], v[114:117]
	v_mfma_f32_16x16x32_bf16 v[110:113], v[164:167], v[236:239], v[110:113]
	v_mfma_f32_16x16x32_bf16 v[106:109], v[172:175], v[236:239], v[106:109]
	v_mfma_f32_16x16x32_bf16 v[102:105], v[164:167], v[244:247], v[102:105]
	v_mfma_f32_16x16x32_bf16 v[98:101], v[172:175], v[244:247], v[98:101]
	v_mfma_f32_16x16x32_bf16 v[126:129], v[168:171], v[200:203], v[126:129]
	v_mfma_f32_16x16x32_bf16 v[122:125], v[176:179], v[200:203], v[122:125]
	v_mfma_f32_16x16x32_bf16 v[118:121], v[168:171], v[220:223], v[118:121]
	v_mfma_f32_16x16x32_bf16 v[114:117], v[176:179], v[220:223], v[114:117]
	v_mfma_f32_16x16x32_bf16 v[110:113], v[168:171], v[240:243], v[110:113]
	v_mfma_f32_16x16x32_bf16 v[106:109], v[176:179], v[240:243], v[106:109]
	v_mfma_f32_16x16x32_bf16 v[102:105], v[168:171], v[248:251], v[102:105]
	v_mfma_f32_16x16x32_bf16 v[98:101], v[176:179], v[248:251], v[98:101]
	v_mfma_f32_16x16x32_bf16 v[94:97], v[180:183], v[196:199], v[94:97]
	v_mfma_f32_16x16x32_bf16 v[90:93], v[188:191], v[196:199], v[90:93]
	v_mfma_f32_16x16x32_bf16 v[86:89], v[180:183], v[204:207], v[86:89]
	v_mfma_f32_16x16x32_bf16 v[82:85], v[188:191], v[204:207], v[82:85]
	v_mfma_f32_16x16x32_bf16 v[78:81], v[180:183], v[236:239], v[78:81]
	v_mfma_f32_16x16x32_bf16 v[74:77], v[188:191], v[236:239], v[74:77]
	v_mfma_f32_16x16x32_bf16 v[70:73], v[180:183], v[244:247], v[70:73]
	v_mfma_f32_16x16x32_bf16 v[66:69], v[188:191], v[244:247], v[66:69]
	v_mfma_f32_16x16x32_bf16 v[94:97], v[184:187], v[200:203], v[94:97]
	v_mfma_f32_16x16x32_bf16 v[90:93], v[192:195], v[200:203], v[90:93]
	v_mfma_f32_16x16x32_bf16 v[86:89], v[184:187], v[220:223], v[86:89]
	v_mfma_f32_16x16x32_bf16 v[82:85], v[192:195], v[220:223], v[82:85]
	v_mfma_f32_16x16x32_bf16 v[78:81], v[184:187], v[240:243], v[78:81]
	v_mfma_f32_16x16x32_bf16 v[74:77], v[192:195], v[240:243], v[74:77]
	v_mfma_f32_16x16x32_bf16 v[70:73], v[184:187], v[248:251], v[70:73]
	v_mfma_f32_16x16x32_bf16 v[66:69], v[192:195], v[248:251], v[66:69]
	s_barrier
	s_add_u32 s100, s24, 0xfffc0080
	s_addc_u32 s101, s25, -1
	s_add_u32 s22, s22, 0x80
	s_addc_u32 s23, s23, 0
	s_add_i32 s24, s46, s28
	s_mov_b32 m0, s24
	ds_read_b128 v[196:199], v162 offset:49152
	ds_read_b128 v[200:203], v162 offset:50176
	ds_read_b128 v[204:207], v162 offset:51200
	ds_read_b128 v[220:223], v162 offset:52224
	global_load_lds_dwordx4 v134, s[22:23] sc0
	s_add_i32 m0, s24, 0x2000
	s_add_i32 s24, s47, s28
	global_load_lds_dwordx4 v130, s[22:23] sc0
	s_add_u32 s22, s22, 0x40000
	s_addc_u32 s23, s23, 0
	s_mov_b32 m0, s24
	ds_read_b128 v[236:239], v162 offset:53248
	global_load_lds_dwordx4 v134, s[22:23] sc0
	s_add_i32 m0, s24, 0x2000
	ds_read_b128 v[240:243], v162 offset:54272
	global_load_lds_dwordx4 v130, s[22:23] sc0
	s_mov_b32 m0, s36
	ds_read_b128 v[244:247], v162 offset:55296
	global_load_lds_dwordx4 v136, s[100:101] sc0
	s_mov_b32 m0, s37
	ds_read_b128 v[248:251], v162 offset:56320
	global_load_lds_dwordx4 v132, s[100:101] sc0
	s_waitcnt vmcnt(8)
	s_waitcnt lgkmcnt(0)
	s_barrier
	v_mfma_f32_16x16x32_bf16 v[62:65], v[164:167], v[196:199], v[62:65]
	v_mfma_f32_16x16x32_bf16 v[58:61], v[172:175], v[196:199], v[58:61]
	v_mfma_f32_16x16x32_bf16 v[54:57], v[164:167], v[204:207], v[54:57]
	v_mfma_f32_16x16x32_bf16 v[50:53], v[172:175], v[204:207], v[50:53]
	v_mfma_f32_16x16x32_bf16 v[46:49], v[164:167], v[236:239], v[46:49]
	v_mfma_f32_16x16x32_bf16 v[42:45], v[172:175], v[236:239], v[42:45]
	v_mfma_f32_16x16x32_bf16 v[38:41], v[164:167], v[244:247], v[38:41]
	v_mfma_f32_16x16x32_bf16 v[34:37], v[172:175], v[244:247], v[34:37]
	v_mfma_f32_16x16x32_bf16 v[62:65], v[168:171], v[200:203], v[62:65]
	v_mfma_f32_16x16x32_bf16 v[58:61], v[176:179], v[200:203], v[58:61]
	v_mfma_f32_16x16x32_bf16 v[54:57], v[168:171], v[220:223], v[54:57]
	v_mfma_f32_16x16x32_bf16 v[50:53], v[176:179], v[220:223], v[50:53]
	v_mfma_f32_16x16x32_bf16 v[46:49], v[168:171], v[240:243], v[46:49]
	v_mfma_f32_16x16x32_bf16 v[42:45], v[176:179], v[240:243], v[42:45]
	v_mfma_f32_16x16x32_bf16 v[38:41], v[168:171], v[248:251], v[38:41]
	v_mfma_f32_16x16x32_bf16 v[34:37], v[176:179], v[248:251], v[34:37]
	v_mfma_f32_16x16x32_bf16 v[30:33], v[180:183], v[196:199], v[30:33]
	v_mfma_f32_16x16x32_bf16 v[26:29], v[188:191], v[196:199], v[26:29]
	v_mfma_f32_16x16x32_bf16 v[22:25], v[180:183], v[204:207], v[22:25]
	v_mfma_f32_16x16x32_bf16 v[18:21], v[188:191], v[204:207], v[18:21]
	v_mfma_f32_16x16x32_bf16 v[14:17], v[180:183], v[236:239], v[14:17]
	v_mfma_f32_16x16x32_bf16 v[10:13], v[188:191], v[236:239], v[10:13]
	v_mfma_f32_16x16x32_bf16 v[6:9], v[180:183], v[244:247], v[6:9]
	v_mfma_f32_16x16x32_bf16 v[2:5], v[188:191], v[244:247], v[2:5]
	v_mfma_f32_16x16x32_bf16 v[30:33], v[184:187], v[200:203], v[30:33]
	v_mfma_f32_16x16x32_bf16 v[26:29], v[192:195], v[200:203], v[26:29]
	v_mfma_f32_16x16x32_bf16 v[22:25], v[184:187], v[220:223], v[22:25]
	v_mfma_f32_16x16x32_bf16 v[18:21], v[192:195], v[220:223], v[18:21]
	v_mfma_f32_16x16x32_bf16 v[14:17], v[184:187], v[240:243], v[14:17]
	v_mfma_f32_16x16x32_bf16 v[10:13], v[192:195], v[240:243], v[10:13]
	v_mfma_f32_16x16x32_bf16 v[6:9], v[184:187], v[248:251], v[6:9]
	v_mfma_f32_16x16x32_bf16 v[2:5], v[192:195], v[248:251], v[2:5]
	s_barrier
	s_add_i32 s45, s45, 2
	s_add_u32 s43, s43, 0x100
	s_addc_u32 s44, s44, 0
	s_add_u32 s20, s20, 0x100
	s_addc_u32 s21, s21, 0
	s_cmp_gt_u32 s45, 13
	s_cbranch_scc0 .LBB0_640
	s_and_b64 vcc, exec, s[8:9]
	s_cbranch_vccz .LBB0_643
	s_barrier
